# NSA attention: wave priority raised per tile around the QK MFMA block (all waves) instead of the static high priority of waves 4-7
# baseline (speedup 1.0000x reference)
.LBB0_4361:
	s_cmp_gt_i32 s44, 15
	s_cselect_b64 s[2:3], -1, 0
	s_cmp_lt_i32 s45, 16
	s_cselect_b64 s[4:5], -1, 0
	s_or_b64 s[2:3], s[2:3], s[4:5]
	s_and_b64 vcc, exec, s[2:3]
	s_cbranch_vccnz .LBB0_4470
	s_cmp_lt_u32 s70, 256
	s_cbranch_scc1 .Lprio_skip_15
.Lprio_skip_15:
	v_mbcnt_hi_u32_b32 v169, -1, v210
	v_mov_b32_e32 v0, v169
	s_mov_b32 s21, 0
	v_add_u32_e32 v1, s70, v0
	s_cmpk_gt_i32 s22, 0x7ff
	v_readfirstlane_b32 s2, v1
	s_cbranch_scc1 .LBB0_4416
	s_abs_i32 s60, s42
	s_waitcnt lgkmcnt(0)
	v_cvt_f32_u32_e32 v4, s60
	v_and_b32_e32 v3, 64, v169
	v_xor_b32_e32 v2, 32, v169
	v_add_u32_e32 v3, 64, v3
	v_cmp_lt_i32_e32 vcc, v2, v3
	v_rcp_iflag_f32_e32 v3, v4
	s_ashr_i32 s56, s42, 31
	v_cndmask_b32_e32 v2, v169, v2, vcc
	v_lshlrev_b32_e32 v175, 2, v2
	v_mul_f32_e32 v2, 0x4f7ffffe, v3
	v_cvt_u32_f32_e32 v2, v2
	s_lshr_b32 s3, s56, 27
	s_add_i32 s3, s42, s3
	s_ashr_i32 s58, s2, 7
	s_lshr_b32 s2, s2, 1
	s_ashr_i32 s57, s3, 5
	s_and_b32 s59, s2, 32
	s_load_dwordx2 s[24:25], s[0:1], 0x190
	s_load_dwordx2 s[2:3], s[0:1], 0x1d8
	s_load_dwordx2 s[26:27], s[0:1], 0x200
	s_load_dwordx4 s[16:19], s[0:1], 0x1f0
	s_sub_i32 s4, 0, s60
	v_readfirstlane_b32 s5, v2
	s_mul_i32 s4, s4, s5
	s_mul_hi_u32 s4, s5, s4
	s_add_i32 s61, s5, s4
	s_waitcnt lgkmcnt(0)
	s_add_u32 s30, s16, 0x2000
	v_and_b32_e32 v168, 31, v0
	v_lshrrev_b32_e32 v0, 2, v0
	s_addc_u32 s31, s17, 0
	v_mov_b32_e32 v1, 0
	v_and_b32_e32 v0, 8, v0
	s_add_u32 s34, s18, 0x2000
	s_mov_b64 s[28:29], 0x2000
	s_addc_u32 s35, s19, 0
	v_lshlrev_b32_e32 v170, 1, v0
	v_mov_b32_e32 v171, v1
	s_movk_i32 s62, 0x60
	v_mov_b64_e32 v[172:173], s[2:3]
	v_mov_b32_e32 v182, 0x60
	v_lshlrev_b32_e32 v183, 3, v168
	s_movk_i32 s63, 0x90
	s_movk_i32 s64, 0xc0
	s_movk_i32 s65, 0xff
	s_mov_b32 s66, 0xff800000
	s_mov_b64 s[36:37], 0x8000
	v_mov_b32_e32 v184, 0x3cf
	v_mov_b32_e32 v185, 0xff800000
	v_mov_b32_e32 v186, 0x7f800000
	s_mov_b32 s67, s22
	s_mov_b32 s68, s22
	s_branch .LBB0_4365

.LBB0_4384:
	v_add3_u32 v0, s20, v135, v136
	s_waitcnt lgkmcnt(0)
	s_barrier
	s_setprio 3
	v_lshrrev_b64 v[232:233], s2, v[120:121]
	v_and_b32_e32 v232, 1, v232
	v_cmp_eq_u32_e64 s[84:85], 0, v232
	s_nop 1
	v_cndmask_b32_e64 v212, v228, v185, s[84:85]
	v_cndmask_b32_e64 v213, v228, v185, s[84:85]
	v_cndmask_b32_e64 v214, v228, v185, s[84:85]
	v_cndmask_b32_e64 v215, v228, v185, s[84:85]
	v_cndmask_b32_e64 v216, v228, v185, s[84:85]
	v_cndmask_b32_e64 v217, v228, v185, s[84:85]
	v_cndmask_b32_e64 v218, v228, v185, s[84:85]
	v_cndmask_b32_e64 v219, v228, v185, s[84:85]
	v_cndmask_b32_e64 v220, v228, v185, s[84:85]
	v_cndmask_b32_e64 v221, v228, v185, s[84:85]
	v_cndmask_b32_e64 v222, v228, v185, s[84:85]
	v_cndmask_b32_e64 v223, v228, v185, s[84:85]
	v_cndmask_b32_e64 v224, v228, v185, s[84:85]
	v_cndmask_b32_e64 v225, v228, v185, s[84:85]
	v_cndmask_b32_e64 v226, v228, v185, s[84:85]
	v_cndmask_b32_e64 v227, v228, v185, s[84:85]
	ds_read_b128 v[2:5], v0
	ds_read_b128 v[18:21], v0 offset:32
	s_waitcnt lgkmcnt(1)
	v_mfma_f32_32x32x16_bf16 v[96:111], v[2:5], v[144:147], v[212:227]
	ds_read_b128 v[2:5], v0 offset:4608
	ds_read_b128 v[22:25], v0 offset:4640
	s_cmp_le_i32 s15, s48
	s_waitcnt lgkmcnt(1)
	v_mfma_f32_32x32x16_bf16 v[2:17], v[2:5], v[144:147], v[212:227]
	v_mfma_f32_32x32x16_bf16 v[96:111], v[18:21], v[148:151], v[96:111]
	s_waitcnt lgkmcnt(0)
	v_mfma_f32_32x32x16_bf16 v[2:17], v[22:25], v[148:151], v[2:17]
	ds_read_b128 v[18:21], v0 offset:64
	ds_read_b128 v[22:25], v0 offset:96
	s_waitcnt lgkmcnt(1)
	v_mfma_f32_32x32x16_bf16 v[96:111], v[18:21], v[152:155], v[96:111]
	ds_read_b128 v[18:21], v0 offset:4672
	ds_read_b128 v[26:29], v0 offset:4704
	s_waitcnt lgkmcnt(1)
	v_mfma_f32_32x32x16_bf16 v[2:17], v[18:21], v[152:155], v[2:17]
	v_mfma_f32_32x32x16_bf16 v[96:111], v[22:25], v[156:159], v[96:111]
	s_waitcnt lgkmcnt(0)
	v_mfma_f32_32x32x16_bf16 v[2:17], v[26:29], v[156:159], v[2:17]
	s_cbranch_scc1 .LBB0_4386
	v_add_u32_e32 v0, s15, v133
	v_subrev_u32_e32 v18, 63, v0
	v_cmp_le_i32_e32 vcc, v18, v132
	s_nop 5
	v_cndmask_b32_e32 v96, v185, v96, vcc
	v_cmp_lt_i32_e32 vcc, v18, v132
	v_subrev_u32_e32 v18, 61, v0
	s_nop 0
	v_cndmask_b32_e32 v97, v185, v97, vcc
	v_cmp_le_i32_e32 vcc, v18, v132
	v_subrev_u32_e32 v18, 60, v0
	s_nop 0
	v_cndmask_b32_e32 v98, v185, v98, vcc
	v_cmp_le_i32_e32 vcc, v18, v132
	v_subrev_u32_e32 v18, 55, v0
	s_nop 0
	v_cndmask_b32_e32 v99, v185, v99, vcc
	v_cmp_le_i32_e32 vcc, v18, v132
	v_subrev_u32_e32 v18, 54, v0
	s_nop 0
	v_cndmask_b32_e32 v100, v185, v100, vcc
	v_cmp_le_i32_e32 vcc, v18, v132
	v_subrev_u32_e32 v18, 53, v0
	s_nop 0
	v_cndmask_b32_e32 v101, v185, v101, vcc
	v_cmp_le_i32_e32 vcc, v18, v132
	v_subrev_u32_e32 v18, 52, v0
	s_nop 0
	v_cndmask_b32_e32 v102, v185, v102, vcc
	v_cmp_le_i32_e32 vcc, v18, v132
	v_subrev_u32_e32 v18, 47, v0
	s_nop 0
	v_cndmask_b32_e32 v103, v185, v103, vcc
	v_cmp_le_i32_e32 vcc, v18, v132
	v_subrev_u32_e32 v18, 46, v0
	s_nop 0
	v_cndmask_b32_e32 v104, v185, v104, vcc
	v_cmp_le_i32_e32 vcc, v18, v132
	v_subrev_u32_e32 v18, 45, v0
	s_nop 0
	v_cndmask_b32_e32 v105, v185, v105, vcc
	v_cmp_le_i32_e32 vcc, v18, v132
	v_subrev_u32_e32 v18, 44, v0
	s_nop 0
	v_cndmask_b32_e32 v106, v185, v106, vcc
	v_cmp_le_i32_e32 vcc, v18, v132
	v_subrev_u32_e32 v18, 39, v0
	s_nop 0
	v_cndmask_b32_e32 v107, v185, v107, vcc
	v_cmp_le_i32_e32 vcc, v18, v132
	v_subrev_u32_e32 v18, 38, v0
	s_nop 0
	v_cndmask_b32_e32 v108, v185, v108, vcc
	v_cmp_le_i32_e32 vcc, v18, v132
	v_subrev_u32_e32 v18, 37, v0
	s_nop 0
	v_cndmask_b32_e32 v109, v185, v109, vcc
	v_cmp_le_i32_e32 vcc, v18, v132
	v_subrev_u32_e32 v18, 36, v0
	s_nop 0
	v_cndmask_b32_e32 v110, v185, v110, vcc
	v_cmp_le_i32_e32 vcc, v18, v132
	v_subrev_u32_e32 v18, 31, v0
	s_nop 0
	v_cndmask_b32_e32 v111, v185, v111, vcc
	v_cmp_le_i32_e32 vcc, v18, v132
	v_subrev_u32_e32 v18, 30, v0
	s_nop 0
	v_cndmask_b32_e32 v2, v185, v2, vcc
	v_cmp_le_i32_e32 vcc, v18, v132
	v_subrev_u32_e32 v18, 29, v0
	s_nop 0
	v_cndmask_b32_e32 v3, v185, v3, vcc
	v_cmp_le_i32_e32 vcc, v18, v132
	v_subrev_u32_e32 v18, 28, v0
	s_nop 0
	v_cndmask_b32_e32 v4, v185, v4, vcc
	v_cmp_le_i32_e32 vcc, v18, v132
	v_subrev_u32_e32 v18, 23, v0
	s_nop 0
	v_cndmask_b32_e32 v5, v185, v5, vcc
	v_cmp_le_i32_e32 vcc, v18, v132
	v_subrev_u32_e32 v18, 22, v0
	s_nop 0
	v_cndmask_b32_e32 v6, v185, v6, vcc
	v_cmp_le_i32_e32 vcc, v18, v132
	v_subrev_u32_e32 v18, 21, v0
	s_nop 0
	v_cndmask_b32_e32 v7, v185, v7, vcc
	v_cmp_le_i32_e32 vcc, v18, v132
	v_subrev_u32_e32 v18, 20, v0
	s_nop 0
	v_cndmask_b32_e32 v8, v185, v8, vcc
	v_cmp_le_i32_e32 vcc, v18, v132
	v_add_u32_e32 v18, -15, v0
	s_nop 0
	v_cndmask_b32_e32 v9, v185, v9, vcc
	v_cmp_le_i32_e32 vcc, v18, v132
	v_add_u32_e32 v18, -14, v0
	s_nop 0
	v_cndmask_b32_e32 v10, v185, v10, vcc
	v_cmp_le_i32_e32 vcc, v18, v132
	v_add_u32_e32 v18, -13, v0
	s_nop 0
	v_cndmask_b32_e32 v11, v185, v11, vcc
	v_cmp_le_i32_e32 vcc, v18, v132
	v_add_u32_e32 v18, -12, v0
	s_nop 0
	v_cndmask_b32_e32 v12, v185, v12, vcc
	v_cmp_le_i32_e32 vcc, v18, v132
	v_add_u32_e32 v18, -7, v0
	s_nop 0
	v_cndmask_b32_e32 v13, v185, v13, vcc
	v_cmp_le_i32_e32 vcc, v18, v132
	v_add_u32_e32 v18, -6, v0
	s_nop 0
	v_cndmask_b32_e32 v14, v185, v14, vcc
	v_cmp_le_i32_e32 vcc, v18, v132
	v_add_u32_e32 v18, -5, v0
	v_add_u32_e32 v0, -4, v0
	v_cndmask_b32_e32 v15, v185, v15, vcc
	v_cmp_le_i32_e32 vcc, v18, v132
	s_nop 1
	v_cndmask_b32_e32 v16, v185, v16, vcc
	v_cmp_le_i32_e32 vcc, v0, v132
	s_nop 1
	v_cndmask_b32_e32 v17, v185, v17, vcc
.LBB0_4386:
	s_setprio 0
	s_nop 8
	s_cmp_eq_u32 s98, 0
	s_cbranch_scc1 .LBB0_4388
	v_max3_f32 v0, v96, s66, v97
	v_max3_f32 v0, v0, v98, v99
	v_max3_f32 v0, v0, v100, v101
	v_max3_f32 v0, v0, v102, v103
	v_max3_f32 v0, v0, v104, v105
	v_max3_f32 v0, v0, v106, v107
	v_max3_f32 v0, v0, v108, v109
	v_max3_f32 v0, v0, v110, v111
	v_max3_f32 v0, v0, v2, v3
	v_max3_f32 v0, v0, v4, v5
	v_max3_f32 v0, v0, v6, v7
	v_max3_f32 v0, v0, v8, v9
	v_max3_f32 v0, v0, v10, v11
	v_max3_f32 v0, v0, v12, v13
	v_max3_f32 v0, v0, v14, v15
	v_max3_f32 v20, v0, v16, v17
	ds_bpermute_b32 v21, v175, v20
	v_lshrrev_b64 v[18:19], s2, v[120:121]
	v_and_b32_e32 v0, 1, v18
	v_cmp_eq_u64_e64 s[2:3], 0, v[0:1]
	s_waitcnt lgkmcnt(0)
	v_max_f32_e32 v18, v21, v21
	v_max_f32_e32 v18, v20, v18
	v_cndmask_b32_e64 v0, v18, v185, s[2:3]
	v_add_f32_e32 v18, 0x41000000, v229
	v_cmp_gt_f32_e32 vcc, v0, v18
	s_cbranch_vccz .LBB0_4388
	v_max_f32_e32 v0, v0, v0
	v_max_f32_e32 v230, v229, v229
	v_max_f32_e32 v230, v230, v0
	v_sub_f32_e32 v231, v230, v228
	v_sub_f32_e32 v0, v229, v230
	v_exp_f32_e32 v0, v0
	s_nop 0
	v_pk_mul_f32 v[94:95], v[94:95], v[0:1] op_sel_hi:[1,0]
	v_pk_mul_f32 v[92:93], v[92:93], v[0:1] op_sel_hi:[1,0]
	v_pk_mul_f32 v[90:91], v[90:91], v[0:1] op_sel_hi:[1,0]
	v_pk_mul_f32 v[88:89], v[88:89], v[0:1] op_sel_hi:[1,0]
	v_pk_mul_f32 v[86:87], v[86:87], v[0:1] op_sel_hi:[1,0]
	v_pk_mul_f32 v[84:85], v[84:85], v[0:1] op_sel_hi:[1,0]
	v_pk_mul_f32 v[82:83], v[82:83], v[0:1] op_sel_hi:[1,0]
	v_pk_mul_f32 v[80:81], v[80:81], v[0:1] op_sel_hi:[1,0]
	v_pk_mul_f32 v[78:79], v[78:79], v[0:1] op_sel_hi:[1,0]
	v_pk_mul_f32 v[76:77], v[76:77], v[0:1] op_sel_hi:[1,0]
	v_pk_mul_f32 v[74:75], v[74:75], v[0:1] op_sel_hi:[1,0]
	v_pk_mul_f32 v[72:73], v[72:73], v[0:1] op_sel_hi:[1,0]
	v_pk_mul_f32 v[70:71], v[70:71], v[0:1] op_sel_hi:[1,0]
	v_pk_mul_f32 v[68:69], v[68:69], v[0:1] op_sel_hi:[1,0]
	v_pk_mul_f32 v[66:67], v[66:67], v[0:1] op_sel_hi:[1,0]
	v_pk_mul_f32 v[64:65], v[64:65], v[0:1] op_sel_hi:[1,0]
	v_mul_f32_e32 v189, v189, v0
	v_mov_b32_e32 v139, v231
	v_xor_b32_e32 v230, 0x80000000, v231
	v_cmp_lt_f32_e32 vcc, 0xf0a18f08, v231
	s_nop 1
	v_cndmask_b32_e32 v230, 0, v230, vcc
	v_add_f32_e32 v229, v231, v230
	v_sub_f32_e32 v231, v230, v228
	v_mov_b32_e32 v228, v230
	v_add_f32_e32 v2, v231, v2
	v_add_f32_e32 v3, v231, v3
	v_add_f32_e32 v4, v231, v4
	v_add_f32_e32 v5, v231, v5
	v_add_f32_e32 v6, v231, v6
	v_add_f32_e32 v7, v231, v7
	v_add_f32_e32 v8, v231, v8
	v_add_f32_e32 v9, v231, v9
	v_add_f32_e32 v10, v231, v10
	v_add_f32_e32 v11, v231, v11
	v_add_f32_e32 v12, v231, v12
	v_add_f32_e32 v13, v231, v13
	v_add_f32_e32 v14, v231, v14
	v_add_f32_e32 v15, v231, v15
	v_add_f32_e32 v16, v231, v16
	v_add_f32_e32 v17, v231, v17
	v_add_f32_e32 v96, v231, v96
	v_add_f32_e32 v97, v231, v97
	v_add_f32_e32 v98, v231, v98
	v_add_f32_e32 v99, v231, v99
	v_add_f32_e32 v100, v231, v100
	v_add_f32_e32 v101, v231, v101
	v_add_f32_e32 v102, v231, v102
	v_add_f32_e32 v103, v231, v103
	v_add_f32_e32 v104, v231, v104
	v_add_f32_e32 v105, v231, v105
	v_add_f32_e32 v106, v231, v106
	v_add_f32_e32 v107, v231, v107
	v_add_f32_e32 v108, v231, v108
	v_add_f32_e32 v109, v231, v109
	v_add_f32_e32 v110, v231, v110
	v_add_f32_e32 v111, v231, v111
	v_cndmask_b32_e32 v139, 0, v139, vcc

.LBB0_4406:
	v_add3_u32 v0, s11, v195, v197
	s_waitcnt lgkmcnt(0)
	s_barrier
	s_setprio 3
	ds_read_b128 v[2:5], v0
	ds_read_b128 v[18:21], v0 offset:32
	s_waitcnt lgkmcnt(1)
	v_mfma_f32_32x32x16_bf16 v[128:143], v[2:5], v[144:147], v[212:227]
	ds_read_b128 v[2:5], v0 offset:4608
	ds_read_b128 v[22:25], v0 offset:4640
	s_add_i32 s12, s9, 63
	s_cmp_ge_i32 s9, s7
	s_cselect_b64 s[2:3], -1, 0
	s_cmp_le_i32 s12, s48
	s_cselect_b64 s[12:13], -1, 0
	s_and_b64 s[2:3], s[2:3], s[12:13]
	s_waitcnt lgkmcnt(1)
	v_mfma_f32_32x32x16_bf16 v[2:17], v[2:5], v[144:147], v[212:227]
	s_and_b64 vcc, exec, s[2:3]
	v_mfma_f32_32x32x16_bf16 v[128:143], v[18:21], v[148:151], v[128:143]
	s_waitcnt lgkmcnt(0)
	v_mfma_f32_32x32x16_bf16 v[2:17], v[22:25], v[148:151], v[2:17]
	ds_read_b128 v[18:21], v0 offset:64
	ds_read_b128 v[22:25], v0 offset:96
	s_waitcnt lgkmcnt(1)
	v_mfma_f32_32x32x16_bf16 v[128:143], v[18:21], v[152:155], v[128:143]
	ds_read_b128 v[18:21], v0 offset:4672
	ds_read_b128 v[26:29], v0 offset:4704
	s_waitcnt lgkmcnt(1)
	v_mfma_f32_32x32x16_bf16 v[2:17], v[18:21], v[152:155], v[2:17]
	v_mfma_f32_32x32x16_bf16 v[128:143], v[22:25], v[156:159], v[128:143]
	s_waitcnt lgkmcnt(0)
	v_mfma_f32_32x32x16_bf16 v[2:17], v[26:29], v[156:159], v[2:17]
	s_cbranch_vccnz .LBB0_4408
	v_add_u32_e32 v0, s9, v194
	v_add_u32_e32 v18, 0x200, v0
	v_cmp_le_i32_e32 vcc, v0, v193
	v_cmp_gt_i32_e64 s[2:3], v18, v193
	s_and_b64 vcc, vcc, s[2:3]
	v_add_u32_e32 v18, 0x201, v0
	s_nop 2
	v_cndmask_b32_e32 v128, v185, v128, vcc
	v_cmp_lt_i32_e32 vcc, v0, v193
	v_cmp_gt_i32_e64 s[2:3], v18, v193
	s_and_b64 vcc, vcc, s[2:3]
	v_add_u32_e32 v18, 2, v0
	v_cndmask_b32_e32 v129, v185, v129, vcc
	v_cmp_le_i32_e32 vcc, v18, v193
	v_add_u32_e32 v18, 0x202, v0
	v_cmp_gt_i32_e64 s[2:3], v18, v193
	s_and_b64 vcc, vcc, s[2:3]
	v_add_u32_e32 v18, 3, v0
	v_cndmask_b32_e32 v130, v185, v130, vcc
	v_cmp_le_i32_e32 vcc, v18, v193
	v_add_u32_e32 v18, 0x203, v0
	v_cmp_gt_i32_e64 s[2:3], v18, v193
	s_and_b64 vcc, vcc, s[2:3]
	v_add_u32_e32 v18, 8, v0
	v_cndmask_b32_e32 v131, v185, v131, vcc
	v_cmp_le_i32_e32 vcc, v18, v193
	v_add_u32_e32 v18, 0x208, v0
	v_cmp_gt_i32_e64 s[2:3], v18, v193
	s_and_b64 vcc, vcc, s[2:3]
	v_add_u32_e32 v18, 9, v0
	v_cndmask_b32_e32 v132, v185, v132, vcc
	v_cmp_le_i32_e32 vcc, v18, v193
	v_add_u32_e32 v18, 0x209, v0
	v_cmp_gt_i32_e64 s[2:3], v18, v193
	s_and_b64 vcc, vcc, s[2:3]
	v_add_u32_e32 v18, 10, v0
	v_cndmask_b32_e32 v133, v185, v133, vcc
	v_cmp_le_i32_e32 vcc, v18, v193
	v_add_u32_e32 v18, 0x20a, v0
	v_cmp_gt_i32_e64 s[2:3], v18, v193
	s_and_b64 vcc, vcc, s[2:3]
	v_add_u32_e32 v18, 11, v0
	v_cndmask_b32_e32 v134, v185, v134, vcc
	v_cmp_le_i32_e32 vcc, v18, v193
	v_add_u32_e32 v18, 0x20b, v0
	v_cmp_gt_i32_e64 s[2:3], v18, v193
	s_and_b64 vcc, vcc, s[2:3]
	v_add_u32_e32 v18, 16, v0
	v_cndmask_b32_e32 v135, v185, v135, vcc
	v_cmp_le_i32_e32 vcc, v18, v193
	v_add_u32_e32 v18, 0x210, v0
	v_cmp_gt_i32_e64 s[2:3], v18, v193
	s_and_b64 vcc, vcc, s[2:3]
	v_add_u32_e32 v18, 17, v0
	v_cndmask_b32_e32 v136, v185, v136, vcc
	v_cmp_le_i32_e32 vcc, v18, v193
	v_add_u32_e32 v18, 0x211, v0
	v_cmp_gt_i32_e64 s[2:3], v18, v193
	s_and_b64 vcc, vcc, s[2:3]
	v_add_u32_e32 v18, 18, v0
	v_cndmask_b32_e32 v137, v185, v137, vcc
	v_cmp_le_i32_e32 vcc, v18, v193
	v_add_u32_e32 v18, 0x212, v0
	v_cmp_gt_i32_e64 s[2:3], v18, v193
	s_and_b64 vcc, vcc, s[2:3]
	v_add_u32_e32 v18, 19, v0
	v_cndmask_b32_e32 v138, v185, v138, vcc
	v_cmp_le_i32_e32 vcc, v18, v193
	v_add_u32_e32 v18, 0x213, v0
	v_cmp_gt_i32_e64 s[2:3], v18, v193
	s_and_b64 vcc, vcc, s[2:3]
	v_add_u32_e32 v18, 24, v0
	v_cndmask_b32_e32 v139, v185, v139, vcc
	v_cmp_le_i32_e32 vcc, v18, v193
	v_add_u32_e32 v18, 0x218, v0
	v_cmp_gt_i32_e64 s[2:3], v18, v193
	s_and_b64 vcc, vcc, s[2:3]
	v_add_u32_e32 v18, 25, v0
	v_cndmask_b32_e32 v140, v185, v140, vcc
	v_cmp_le_i32_e32 vcc, v18, v193
	v_add_u32_e32 v18, 0x219, v0
	v_cmp_gt_i32_e64 s[2:3], v18, v193
	s_and_b64 vcc, vcc, s[2:3]
	v_add_u32_e32 v18, 26, v0
	v_cndmask_b32_e32 v141, v185, v141, vcc
	v_cmp_le_i32_e32 vcc, v18, v193
	v_add_u32_e32 v18, 0x21a, v0
	v_cmp_gt_i32_e64 s[2:3], v18, v193
	s_and_b64 vcc, vcc, s[2:3]
	v_add_u32_e32 v18, 27, v0
	v_cndmask_b32_e32 v142, v185, v142, vcc
	v_cmp_le_i32_e32 vcc, v18, v193
	v_add_u32_e32 v18, 0x21b, v0
	v_cmp_gt_i32_e64 s[2:3], v18, v193
	s_and_b64 vcc, vcc, s[2:3]
	v_add_u32_e32 v18, 32, v0
	v_cndmask_b32_e32 v143, v185, v143, vcc
	v_cmp_le_i32_e32 vcc, v18, v193
	v_add_u32_e32 v18, 0x220, v0
	v_cmp_gt_i32_e64 s[2:3], v18, v193
	s_and_b64 vcc, vcc, s[2:3]
	v_add_u32_e32 v18, 33, v0
	v_cndmask_b32_e32 v2, v185, v2, vcc
	v_cmp_le_i32_e32 vcc, v18, v193
	v_add_u32_e32 v18, 0x221, v0
	v_cmp_gt_i32_e64 s[2:3], v18, v193
	s_and_b64 vcc, vcc, s[2:3]
	v_add_u32_e32 v18, 34, v0
	v_cndmask_b32_e32 v3, v185, v3, vcc
	v_cmp_le_i32_e32 vcc, v18, v193
	v_add_u32_e32 v18, 0x222, v0
	v_cmp_gt_i32_e64 s[2:3], v18, v193
	s_and_b64 vcc, vcc, s[2:3]
	v_add_u32_e32 v18, 35, v0
	v_cndmask_b32_e32 v4, v185, v4, vcc
	v_cmp_le_i32_e32 vcc, v18, v193
	v_add_u32_e32 v18, 0x223, v0
	v_cmp_gt_i32_e64 s[2:3], v18, v193
	s_and_b64 vcc, vcc, s[2:3]
	v_add_u32_e32 v18, 40, v0
	v_cndmask_b32_e32 v5, v185, v5, vcc
	v_cmp_le_i32_e32 vcc, v18, v193
	v_add_u32_e32 v18, 0x228, v0
	v_cmp_gt_i32_e64 s[2:3], v18, v193
	s_and_b64 vcc, vcc, s[2:3]
	v_add_u32_e32 v18, 41, v0
	v_cndmask_b32_e32 v6, v185, v6, vcc
	v_cmp_le_i32_e32 vcc, v18, v193
	v_add_u32_e32 v18, 0x229, v0
	v_cmp_gt_i32_e64 s[2:3], v18, v193
	s_and_b64 vcc, vcc, s[2:3]
	v_add_u32_e32 v18, 42, v0
	v_cndmask_b32_e32 v7, v185, v7, vcc
	v_cmp_le_i32_e32 vcc, v18, v193
	v_add_u32_e32 v18, 0x22a, v0
	v_cmp_gt_i32_e64 s[2:3], v18, v193
	s_and_b64 vcc, vcc, s[2:3]
	v_add_u32_e32 v18, 43, v0
	v_cndmask_b32_e32 v8, v185, v8, vcc
	v_cmp_le_i32_e32 vcc, v18, v193
	v_add_u32_e32 v18, 0x22b, v0
	v_cmp_gt_i32_e64 s[2:3], v18, v193
	s_and_b64 vcc, vcc, s[2:3]
	v_add_u32_e32 v18, 48, v0
	v_cndmask_b32_e32 v9, v185, v9, vcc
	v_cmp_le_i32_e32 vcc, v18, v193
	v_add_u32_e32 v18, 0x230, v0
	v_cmp_gt_i32_e64 s[2:3], v18, v193
	s_and_b64 vcc, vcc, s[2:3]
	v_add_u32_e32 v18, 49, v0
	v_cndmask_b32_e32 v10, v185, v10, vcc
	v_cmp_le_i32_e32 vcc, v18, v193
	v_add_u32_e32 v18, 0x231, v0
	v_cmp_gt_i32_e64 s[2:3], v18, v193
	s_and_b64 vcc, vcc, s[2:3]
	v_add_u32_e32 v18, 50, v0
	v_cndmask_b32_e32 v11, v185, v11, vcc
	v_cmp_le_i32_e32 vcc, v18, v193
	v_add_u32_e32 v18, 0x232, v0
	v_cmp_gt_i32_e64 s[2:3], v18, v193
	s_and_b64 vcc, vcc, s[2:3]
	v_add_u32_e32 v18, 51, v0
	v_cndmask_b32_e32 v12, v185, v12, vcc
	v_cmp_le_i32_e32 vcc, v18, v193
	v_add_u32_e32 v18, 0x233, v0
	v_cmp_gt_i32_e64 s[2:3], v18, v193
	s_and_b64 vcc, vcc, s[2:3]
	v_add_u32_e32 v18, 56, v0
	v_cndmask_b32_e32 v13, v185, v13, vcc
	v_cmp_le_i32_e32 vcc, v18, v193
	v_add_u32_e32 v18, 0x238, v0
	v_cmp_gt_i32_e64 s[2:3], v18, v193
	s_and_b64 vcc, vcc, s[2:3]
	v_add_u32_e32 v18, 57, v0
	v_cndmask_b32_e32 v14, v185, v14, vcc
	v_cmp_le_i32_e32 vcc, v18, v193
	v_add_u32_e32 v18, 0x239, v0
	v_cmp_gt_i32_e64 s[2:3], v18, v193
	s_and_b64 vcc, vcc, s[2:3]
	v_add_u32_e32 v18, 58, v0
	v_cndmask_b32_e32 v15, v185, v15, vcc
	v_cmp_le_i32_e32 vcc, v18, v193
	v_add_u32_e32 v18, 0x23a, v0
	v_cmp_gt_i32_e64 s[2:3], v18, v193
	s_and_b64 vcc, vcc, s[2:3]
	v_add_u32_e32 v18, 59, v0
	v_add_u32_e32 v0, 0x23b, v0
	v_cndmask_b32_e32 v16, v185, v16, vcc
	v_cmp_le_i32_e32 vcc, v18, v193
	v_cmp_gt_i32_e64 s[2:3], v0, v193
	s_and_b64 vcc, vcc, s[2:3]
	v_cndmask_b32_e32 v17, v185, v17, vcc
.LBB0_4408:
	s_setprio 0
	s_nop 8
	s_cmp_eq_u32 s98, 0
	s_cbranch_scc1 .LBB0_4403
	v_max3_f32 v0, v128, s66, v129
	v_max3_f32 v0, v0, v130, v131
	v_max3_f32 v0, v0, v132, v133
	v_max3_f32 v0, v0, v134, v135
	v_max3_f32 v0, v0, v136, v137
	v_max3_f32 v0, v0, v138, v139
	v_max3_f32 v0, v0, v140, v141
	v_max3_f32 v0, v0, v142, v143
	v_max3_f32 v0, v0, v2, v3
	v_max3_f32 v0, v0, v4, v5
	v_max3_f32 v0, v0, v6, v7
	v_max3_f32 v0, v0, v8, v9
	v_max3_f32 v0, v0, v10, v11
	v_max3_f32 v0, v0, v12, v13
	v_max3_f32 v0, v0, v14, v15
	v_max3_f32 v0, v0, v16, v17
	ds_bpermute_b32 v18, v175, v0
	s_waitcnt lgkmcnt(0)
	v_max_f32_e32 v18, v18, v18
	v_max_f32_e32 v0, v0, v18
	v_add_f32_e32 v18, 0x41000000, v229
	v_cmp_gt_f32_e32 vcc, v0, v18
	s_cbranch_vccz .LBB0_4403
	v_max_f32_e32 v0, v0, v0
	v_max_f32_e32 v230, v229, v229
	v_max_f32_e32 v230, v230, v0
	v_sub_f32_e32 v231, v230, v228
	v_sub_f32_e32 v0, v229, v230
	v_exp_f32_e32 v0, v0
	s_nop 0
	v_pk_mul_f32 v[126:127], v[126:127], v[0:1] op_sel_hi:[1,0]
	v_pk_mul_f32 v[124:125], v[124:125], v[0:1] op_sel_hi:[1,0]
	v_pk_mul_f32 v[122:123], v[122:123], v[0:1] op_sel_hi:[1,0]
	v_pk_mul_f32 v[120:121], v[120:121], v[0:1] op_sel_hi:[1,0]
	v_pk_mul_f32 v[118:119], v[118:119], v[0:1] op_sel_hi:[1,0]
	v_pk_mul_f32 v[116:117], v[116:117], v[0:1] op_sel_hi:[1,0]
	v_pk_mul_f32 v[114:115], v[114:115], v[0:1] op_sel_hi:[1,0]
	v_pk_mul_f32 v[112:113], v[112:113], v[0:1] op_sel_hi:[1,0]
	v_pk_mul_f32 v[110:111], v[110:111], v[0:1] op_sel_hi:[1,0]
	v_pk_mul_f32 v[108:109], v[108:109], v[0:1] op_sel_hi:[1,0]
	v_pk_mul_f32 v[106:107], v[106:107], v[0:1] op_sel_hi:[1,0]
	v_pk_mul_f32 v[104:105], v[104:105], v[0:1] op_sel_hi:[1,0]
	v_pk_mul_f32 v[102:103], v[102:103], v[0:1] op_sel_hi:[1,0]
	v_pk_mul_f32 v[100:101], v[100:101], v[0:1] op_sel_hi:[1,0]
	v_pk_mul_f32 v[98:99], v[98:99], v[0:1] op_sel_hi:[1,0]
	v_pk_mul_f32 v[96:97], v[96:97], v[0:1] op_sel_hi:[1,0]
	v_mul_f32_e32 v192, v192, v0
	v_mov_b32_e32 v200, v231
	v_xor_b32_e32 v230, 0x80000000, v231
	v_cmp_lt_f32_e32 vcc, 0xf0a18f08, v231
	s_nop 1
	v_cndmask_b32_e32 v230, 0, v230, vcc
	v_add_f32_e32 v229, v231, v230
	v_sub_f32_e32 v231, v230, v228
	v_mov_b32_e32 v228, v230
	v_add_f32_e32 v2, v231, v2
	v_add_f32_e32 v3, v231, v3
	v_add_f32_e32 v4, v231, v4
	v_add_f32_e32 v5, v231, v5
	v_add_f32_e32 v6, v231, v6
	v_add_f32_e32 v7, v231, v7
	v_add_f32_e32 v8, v231, v8
	v_add_f32_e32 v9, v231, v9
	v_add_f32_e32 v10, v231, v10
	v_add_f32_e32 v11, v231, v11
	v_add_f32_e32 v12, v231, v12
	v_add_f32_e32 v13, v231, v13
	v_add_f32_e32 v14, v231, v14
	v_add_f32_e32 v15, v231, v15
	v_add_f32_e32 v16, v231, v16
	v_add_f32_e32 v17, v231, v17
	v_add_f32_e32 v128, v231, v128
	v_add_f32_e32 v129, v231, v129
	v_add_f32_e32 v130, v231, v130
	v_add_f32_e32 v131, v231, v131
	v_add_f32_e32 v132, v231, v132
	v_add_f32_e32 v133, v231, v133
	v_add_f32_e32 v134, v231, v134
	v_add_f32_e32 v135, v231, v135
	v_add_f32_e32 v136, v231, v136
	v_add_f32_e32 v137, v231, v137
	v_add_f32_e32 v138, v231, v138
	v_add_f32_e32 v139, v231, v139
	v_add_f32_e32 v140, v231, v140
	v_add_f32_e32 v141, v231, v141
	v_add_f32_e32 v142, v231, v142
	v_add_f32_e32 v143, v231, v143
	v_mov_b32_e32 v212, v230
	v_mov_b32_e32 v213, v230
	v_mov_b32_e32 v214, v230
	v_mov_b32_e32 v215, v230
	v_mov_b32_e32 v216, v230
	v_mov_b32_e32 v217, v230
	v_mov_b32_e32 v218, v230
	v_mov_b32_e32 v219, v230
	v_mov_b32_e32 v220, v230
	v_mov_b32_e32 v221, v230
	v_mov_b32_e32 v222, v230
	v_mov_b32_e32 v223, v230
	v_mov_b32_e32 v224, v230
	v_mov_b32_e32 v225, v230
	v_mov_b32_e32 v226, v230
	v_mov_b32_e32 v227, v230
	v_cndmask_b32_e32 v200, 0, v200, vcc
	s_branch .LBB0_4403
